# all stores before the three grid barriers made sc1 write-through (P0 dword stores, p2_pre stores) and the leaders buffer_wbl2 removed (atomics are memory-side; write-through stores need no release fen
# baseline (speedup 1.0000x reference)
.LBB0_26:
	s_or_b64 exec, exec, s[4:5]
	v_mul_f32_e32 v2, v19, v19
	v_fmamk_f32 v16, v2, 0xb94c1982, v8
	v_fmaak_f32 v16, v2, v16, 0xbe2aaa9d
	v_mul_f32_e32 v16, v2, v16
	v_fmac_f32_e32 v19, v19, v16
	v_fmamk_f32 v16, v2, 0x37d75334, v9
	v_fmaak_f32 v16, v2, v16, 0x3d2aabf7
	v_fmaak_f32 v16, v2, v16, 0xbf000004
	v_fma_f32 v2, v2, v16, 1.0
	v_and_b32_e32 v16, 1, v18
	v_cmp_eq_u32_e64 s[4:5], 0, v16
	v_lshlrev_b32_e32 v16, 30, v18
	v_and_b32_e32 v16, 0x80000000, v16
	v_xor_b32_e32 v14, v15, v14
	v_cndmask_b32_e64 v2, v2, v19, s[4:5]
	v_xor_b32_e32 v14, v14, v16
	v_xor_b32_e32 v2, v14, v2
	v_add_u32_e32 v13, s31, v13
	v_cndmask_b32_e32 v2, v12, v2, vcc
	v_cmp_lt_i32_e32 vcc, s47, v13
	s_or_b64 s[20:21], vcc, s[20:21]
	global_store_dword v[6:7], v2, off offset:32 sc1
	s_andn2_b64 exec, exec, s[20:21]
	s_cbranch_execz .LBB0_35

.LBB0_29:
	s_or_saveexec_b64 s[4:5], s[26:27]
	v_mul_f32_e64 v2, |v14|, s43
	v_rndne_f32_e32 v2, v2
	s_xor_b64 exec, exec, s[4:5]
	v_cvt_i32_f32_e32 v18, v2
	v_fma_f32 v19, v2, s44, |v14|
	v_fmac_f32_e32 v19, 0xb3a22168, v2
	v_fmac_f32_e32 v19, 0xa7c234c4, v2
	s_or_b64 exec, exec, s[4:5]
	v_mul_f32_e32 v20, v19, v19
	v_fmamk_f32 v21, v20, 0xb94c1982, v8
	v_fmaak_f32 v21, v20, v21, 0xbe2aaa9d
	v_mul_f32_e32 v21, v20, v21
	v_fmac_f32_e32 v19, v19, v21
	v_fmamk_f32 v21, v20, 0x37d75334, v9
	v_fmaak_f32 v21, v20, v21, 0x3d2aabf7
	v_fmaak_f32 v21, v20, v21, 0xbf000004
	v_fma_f32 v20, v20, v21, 1.0
	v_and_b32_e32 v21, 1, v18
	v_cmp_eq_u32_e32 vcc, 0, v21
	v_ashrrev_i32_e32 v7, 31, v6
	v_lshlrev_b32_e32 v18, 30, v18
	v_cndmask_b32_e64 v19, -v19, v20, vcc
	v_lshlrev_b64 v[6:7], 6, v[6:7]
	v_bitop3_b32 v18, v18, v19, s45 bitop3:0x6c
	v_cmp_class_f32_e64 vcc, v14, s46
	v_lshl_add_u64 v[6:7], v[4:5], 0, v[6:7]
	s_nop 0
	v_cndmask_b32_e32 v18, v12, v18, vcc
	global_store_dword v[6:7], v18, off sc1
	s_and_saveexec_b64 s[4:5], s[12:13]
	s_xor_b64 s[26:27], exec, s[4:5]
	s_cbranch_execz .LBB0_33
	v_cmp_lt_u32_e64 s[4:5], 63, v17
	v_mad_u64_u32 v[18:19], s[12:13], v16, s35, 0
	s_nop 0
	v_cndmask_b32_e64 v2, 0, v10, s[4:5]
	v_add_u32_e32 v2, v2, v17
	v_cmp_lt_u32_e64 s[6:7], 31, v2
	s_nop 1
	v_cndmask_b32_e64 v17, 0, v11, s[6:7]
	v_add_u32_e32 v2, v17, v2
	v_cmp_lt_u32_e64 s[8:9], 31, v2
	s_nop 1
	v_cndmask_b32_e64 v17, 0, v11, s[8:9]
	v_add_u32_e32 v30, v17, v2
	v_mov_b32_e32 v2, v19
	v_mad_u64_u32 v[20:21], s[12:13], v16, s36, v[2:3]
	v_mov_b32_e32 v2, v21
	v_mad_u64_u32 v[22:23], s[12:13], v16, s37, v[2:3]
	v_mov_b32_e32 v2, v23
	v_mad_u64_u32 v[24:25], s[12:13], v16, s38, v[2:3]
	v_mov_b32_e32 v2, v25
	v_mad_u64_u32 v[26:27], s[12:13], v16, s39, v[2:3]
	v_mov_b32_e32 v2, v27
	v_mad_u64_u32 v[28:29], s[12:13], v16, s40, v[2:3]
	v_mov_b32_e32 v2, v29
	v_mad_u64_u32 v[16:17], s[12:13], v16, s41, v[2:3]
	v_cndmask_b32_e64 v19, v28, v24, s[4:5]
	v_cndmask_b32_e64 v2, v16, v26, s[4:5]
	v_cndmask_b32_e64 v17, v17, v28, s[4:5]
	v_cndmask_b32_e64 v16, v2, v19, s[6:7]
	v_cndmask_b32_e64 v2, v17, v2, s[6:7]
	v_cndmask_b32_e64 v17, v26, v22, s[4:5]
	v_cndmask_b32_e64 v19, v19, v17, s[6:7]
	v_cndmask_b32_e64 v20, v24, v20, s[4:5]
	v_cndmask_b32_e64 v2, v2, v16, s[8:9]
	v_cndmask_b32_e64 v16, v16, v19, s[8:9]
	v_sub_u32_e32 v21, 32, v30
	v_cndmask_b32_e64 v17, v17, v20, s[6:7]
	v_alignbit_b32 v23, v2, v16, v21
	v_cmp_eq_u32_e64 s[12:13], 0, v30
	v_cndmask_b32_e64 v19, v19, v17, s[8:9]
	v_cndmask_b32_e64 v18, v22, v18, s[4:5]
	v_cndmask_b32_e64 v2, v23, v2, s[12:13]
	v_alignbit_b32 v23, v16, v19, v21
	v_cndmask_b32_e64 v16, v23, v16, s[12:13]
	v_bfe_u32 v25, v2, 29, 1
	v_cndmask_b32_e64 v18, v20, v18, s[6:7]
	v_alignbit_b32 v23, v2, v16, 30
	v_sub_u32_e32 v26, 0, v25
	v_cndmask_b32_e64 v17, v17, v18, s[8:9]
	v_xor_b32_e32 v23, v23, v26
	v_alignbit_b32 v18, v19, v17, v21
	v_cndmask_b32_e64 v18, v18, v19, s[12:13]
	v_ffbh_u32_e32 v19, v23
	v_alignbit_b32 v16, v16, v18, 30
	v_min_u32_e32 v19, 32, v19
	v_alignbit_b32 v17, v18, v17, 30
	v_xor_b32_e32 v16, v16, v26
	v_sub_u32_e32 v20, 31, v19
	v_xor_b32_e32 v17, v17, v26
	v_alignbit_b32 v21, v23, v16, v20
	v_alignbit_b32 v16, v16, v17, v20
	v_alignbit_b32 v17, v21, v16, 9
	v_ffbh_u32_e32 v18, v17
	v_min_u32_e32 v18, 32, v18
	v_lshrrev_b32_e32 v24, 29, v2
	v_not_b32_e32 v20, v18
	v_alignbit_b32 v16, v17, v16, v20
	v_lshlrev_b32_e32 v17, 31, v24
	v_or_b32_e32 v20, 0x33000000, v17
	v_add_lshl_u32 v18, v18, v19, 23
	v_lshrrev_b32_e32 v16, 9, v16
	v_sub_u32_e32 v18, v20, v18
	v_or_b32_e32 v17, 0.5, v17
	v_lshlrev_b32_e32 v19, 23, v19
	v_or_b32_e32 v16, v18, v16
	v_lshrrev_b32_e32 v18, 9, v21
	v_sub_u32_e32 v17, v17, v19
	v_or_b32_e32 v17, v18, v17
	v_mul_f32_e32 v18, 0x3fc90fda, v17
	v_fma_f32 v19, v17, s42, -v18
	v_fmac_f32_e32 v19, 0x33a22168, v17
	v_fmac_f32_e32 v19, 0x3fc90fda, v16
	v_lshrrev_b32_e32 v2, 30, v2
	v_add_f32_e32 v19, v18, v19
	v_add_u32_e32 v18, v25, v2

.LBB0_38:
	v_add_u32_e32 v7, -2, v7
	v_ashrrev_i32_e32 v9, 31, v3
	v_mov_b32_e32 v8, v3
	v_ashrrev_i32_e32 v11, 31, v2
	v_mov_b32_e32 v10, v2
	v_cmp_eq_u32_e32 vcc, 0, v7
	v_add_u32_e32 v3, s20, v3
	v_add_u32_e32 v2, s9, v2
	v_lshl_add_u64 v[10:11], v[10:11], 2, s[12:13]
	v_lshl_add_u64 v[8:9], v[8:9], 2, s[12:13]
	s_or_b64 s[18:19], vcc, s[18:19]
	global_store_dword v[10:11], v6, off sc1
	global_store_dword v[8:9], v6, off sc1
	s_andn2_b64 exec, exec, s[18:19]
	s_cbranch_execnz .LBB0_38
	s_or_b64 exec, exec, s[18:19]
	v_mad_u64_u32 v[0:1], s[12:13], v5, s8, v[0:1]
	v_cmp_ne_u32_e32 vcc, v4, v5
	s_orn2_b64 s[12:13], vcc, exec

.LBB0_42:
	v_add_u32_e32 v0, s8, v0
	v_cmp_lt_i32_e32 vcc, s9, v0
	global_store_dword v[2:3], v1, off sc1
	s_or_b64 s[12:13], vcc, s[12:13]
	v_lshl_add_u64 v[2:3], v[2:3], 0, s[4:5]
	s_andn2_b64 exec, exec, s[12:13]
	s_cbranch_execnz .LBB0_42

.LBB0_75:
	s_andn2_saveexec_b64 s[12:13], s[12:13]
	s_cbranch_execz .LBB0_95
	s_mov_b64 s[12:13], exec
	s_waitcnt lgkmcnt(0)
	s_waitcnt vmcnt(0)
	v_mbcnt_lo_u32_b32 v1, s12, 0
	v_mbcnt_hi_u32_b32 v1, s13, v1
	v_cmp_eq_u32_e32 vcc, 0, v1
	s_and_saveexec_b64 s[16:17], vcc
	s_cbranch_execz .LBB0_78
	s_bcnt1_i32_b64 s12, s[12:13]
	v_mov_b32_e32 v2, 0x7000
	v_mov_b32_e32 v3, s12
	global_atomic_add v2, v2, v3, s[6:7] offset:1024 sc0

.LBB0_342:
	v_lshl_add_u64 v[102:103], v[78:79], 0, s[18:19]
	v_lshl_add_u64 v[104:105], v[76:77], 0, s[18:19]
	v_lshl_add_u64 v[106:107], v[74:75], 0, s[18:19]
	v_lshl_add_u64 v[108:109], v[72:73], 0, s[18:19]
	v_lshl_add_u64 v[110:111], v[70:71], 0, s[18:19]
	v_lshl_add_u64 v[112:113], v[68:69], 0, s[18:19]
	v_lshl_add_u64 v[114:115], v[66:67], 0, s[18:19]
	v_lshl_add_u64 v[116:117], v[64:65], 0, s[18:19]
	v_lshl_add_u64 v[118:119], v[62:63], 0, s[18:19]
	v_lshl_add_u64 v[120:121], v[60:61], 0, s[18:19]
	v_lshl_add_u64 v[122:123], v[58:59], 0, s[18:19]
	v_lshl_add_u64 v[124:125], v[56:57], 0, s[18:19]
	v_lshl_add_u64 v[126:127], v[54:55], 0, s[18:19]
	v_lshl_add_u64 v[128:129], v[52:53], 0, s[18:19]
	v_lshl_add_u64 v[130:131], v[50:51], 0, s[18:19]
	v_lshl_add_u64 v[132:133], v[48:49], 0, s[18:19]
	global_load_dword v102, v[102:103], off nt
	s_nop 0
	global_load_dword v103, v[104:105], off nt
	s_nop 0
	global_load_dword v104, v[106:107], off nt
	global_load_dword v105, v[108:109], off nt
	s_nop 0
	global_load_dword v106, v[110:111], off nt
	global_load_dword v107, v[112:113], off nt
	global_load_dword v108, v[114:115], off nt
	global_load_dword v109, v[116:117], off nt
	s_nop 0
	global_load_dword v110, v[118:119], off nt
	global_load_dword v111, v[120:121], off nt
	global_load_dword v112, v[122:123], off nt
	global_load_dword v113, v[124:125], off nt
	global_load_dword v114, v[126:127], off nt
	global_load_dword v115, v[128:129], off nt
	global_load_dword v116, v[130:131], off nt
	global_load_dword v117, v[132:133], off nt
	s_add_u32 s18, s18, 0x20000
	s_addc_u32 s19, s19, 0
	v_add_u32_e32 v118, 0x400, v17
	v_add_u32_e32 v119, 0x800, v17
	v_add_u32_e32 v120, 0xc00, v17
	s_cmp_lg_u32 s18, 0x40000
	s_waitcnt vmcnt(14)
	ds_write2_b32 v17, v102, v103 offset1:66
	s_waitcnt vmcnt(12)
	ds_write2_b32 v17, v104, v105 offset0:132 offset1:198
	s_waitcnt vmcnt(10)
	ds_write2_b32 v118, v106, v107 offset0:8 offset1:74
	s_waitcnt vmcnt(8)
	ds_write2_b32 v118, v108, v109 offset0:140 offset1:206
	s_waitcnt vmcnt(6)
	ds_write2_b32 v119, v110, v111 offset0:16 offset1:82
	s_waitcnt vmcnt(4)
	ds_write2_b32 v119, v112, v113 offset0:148 offset1:214
	s_waitcnt vmcnt(2)
	ds_write2_b32 v120, v114, v115 offset0:24 offset1:90
	s_waitcnt vmcnt(0)
	ds_write2_b32 v120, v116, v117 offset0:156 offset1:222
	v_add_u32_e32 v17, 0x1080, v17
	s_cbranch_scc1 .LBB0_342
	s_waitcnt lgkmcnt(0)
	ds_read2_b32 v[52:53], v82 offset1:8
	ds_read2_b32 v[56:57], v82 offset0:33 offset1:41
	ds_read2_b32 v[58:59], v82 offset0:66 offset1:74
	ds_read2_b32 v[60:61], v82 offset0:99 offset1:107
	ds_read2_b32 v[62:63], v82 offset0:132 offset1:140
	s_waitcnt lgkmcnt(4)
	v_bfe_u32 v17, v52, 16, 1
	v_add3_u32 v17, v52, v17, s26
	s_waitcnt lgkmcnt(3)
	v_bfe_u32 v48, v56, 16, 1
	v_lshrrev_b32_e32 v17, 16, v17
	v_add3_u32 v48, v56, v48, s26
	ds_read2_b32 v[64:65], v82 offset0:165 offset1:173
	v_and_or_b32 v48, v48, s27, v17
	s_waitcnt lgkmcnt(3)
	v_bfe_u32 v17, v58, 16, 1
	v_add3_u32 v17, v58, v17, s26
	s_waitcnt lgkmcnt(2)
	v_bfe_u32 v49, v60, 16, 1
	ds_read2_b32 v[66:67], v82 offset0:198 offset1:206
	v_lshrrev_b32_e32 v17, 16, v17
	v_add3_u32 v49, v60, v49, s26
	ds_read2_b32 v[68:69], v82 offset0:231 offset1:239
	v_and_or_b32 v49, v49, s27, v17
	s_waitcnt lgkmcnt(3)
	v_bfe_u32 v17, v62, 16, 1
	v_add3_u32 v17, v62, v17, s26
	s_waitcnt lgkmcnt(2)
	v_bfe_u32 v50, v64, 16, 1
	v_lshrrev_b32_e32 v17, 16, v17
	v_add3_u32 v50, v64, v50, s26
	v_and_or_b32 v50, v50, s27, v17
	s_waitcnt lgkmcnt(1)
	v_bfe_u32 v17, v66, 16, 1
	s_lshl_b32 s18, s28, 5
	v_add3_u32 v17, v66, v17, s26
	s_waitcnt lgkmcnt(0)
	v_bfe_u32 v51, v68, 16, 1
	s_and_b32 s16, s21, 0x1c0
	s_and_b32 s18, s18, 0x3e0
	v_lshrrev_b32_e32 v17, 16, v17
	v_add3_u32 v51, v68, v51, s26
	s_lshl_b32 s16, s16, 1
	v_and_or_b32 v51, v51, s27, v17
	v_or_b32_e32 v17, s18, v81
	v_lshl_add_u64 v[54:55], v[4:5], 0, s[16:17]
	v_lshlrev_b32_e32 v70, 9, v17
	v_mov_b32_e32 v71, v3
	v_lshl_add_u64 v[70:71], v[54:55], 0, v[70:71]
	v_bfe_u32 v17, v53, 16, 1
	global_store_dwordx4 v[70:71], v[48:51], off sc1
	v_add3_u32 v17, v53, v17, s26
	v_lshrrev_b32_e32 v17, 16, v17
	v_bfe_u32 v48, v57, 16, 1
	v_add3_u32 v48, v57, v48, s26
	v_and_or_b32 v48, v48, s27, v17
	v_bfe_u32 v17, v59, 16, 1
	v_add3_u32 v17, v59, v17, s26
	v_bfe_u32 v49, v61, 16, 1
	v_lshrrev_b32_e32 v17, 16, v17
	v_add3_u32 v49, v61, v49, s26
	v_and_or_b32 v49, v49, s27, v17
	v_bfe_u32 v17, v63, 16, 1
	v_add3_u32 v17, v63, v17, s26
	v_bfe_u32 v50, v65, 16, 1
	v_lshrrev_b32_e32 v17, 16, v17
	v_add3_u32 v50, v65, v50, s26
	v_and_or_b32 v50, v50, s27, v17
	v_bfe_u32 v17, v67, 16, 1
	v_add3_u32 v17, v67, v17, s26
	v_bfe_u32 v51, v69, 16, 1
	v_lshrrev_b32_e32 v17, 16, v17
	v_add3_u32 v51, v69, v51, s26
	v_and_or_b32 v51, v51, s27, v17
	v_or_b32_e32 v17, s18, v83
	v_lshlrev_b32_e32 v52, 9, v17
	v_mov_b32_e32 v53, v3
	ds_read2_b32 v[56:57], v82 offset0:16 offset1:24
	v_lshl_add_u64 v[52:53], v[54:55], 0, v[52:53]
	global_store_dwordx4 v[52:53], v[48:51], off sc1
	ds_read2_b32 v[52:53], v82 offset0:49 offset1:57
	ds_read2_b32 v[58:59], v82 offset0:82 offset1:90
	ds_read2_b32 v[60:61], v82 offset0:115 offset1:123
	s_waitcnt lgkmcnt(3)
	v_bfe_u32 v17, v56, 16, 1
	v_add3_u32 v17, v56, v17, s26
	s_waitcnt lgkmcnt(2)
	v_bfe_u32 v48, v52, 16, 1
	ds_read2_b32 v[62:63], v82 offset0:148 offset1:156
	v_lshrrev_b32_e32 v17, 16, v17
	v_add3_u32 v48, v52, v48, s26
	ds_read2_b32 v[64:65], v82 offset0:181 offset1:189
	v_and_or_b32 v48, v48, s27, v17
	s_waitcnt lgkmcnt(3)
	v_bfe_u32 v17, v58, 16, 1
	v_add3_u32 v17, v58, v17, s26
	s_waitcnt lgkmcnt(2)
	v_bfe_u32 v49, v60, 16, 1
	ds_read2_b32 v[66:67], v82 offset0:214 offset1:222
	v_lshrrev_b32_e32 v17, 16, v17
	v_add3_u32 v49, v60, v49, s26
	ds_read2_b32 v[68:69], v82 offset0:247 offset1:255
	v_and_or_b32 v49, v49, s27, v17
	s_waitcnt lgkmcnt(3)
	v_bfe_u32 v17, v62, 16, 1
	v_add3_u32 v17, v62, v17, s26
	s_waitcnt lgkmcnt(2)
	v_bfe_u32 v50, v64, 16, 1
	v_lshrrev_b32_e32 v17, 16, v17
	v_add3_u32 v50, v64, v50, s26
	v_and_or_b32 v50, v50, s27, v17
	s_waitcnt lgkmcnt(1)
	v_bfe_u32 v17, v66, 16, 1
	v_add3_u32 v17, v66, v17, s26
	s_waitcnt lgkmcnt(0)
	v_bfe_u32 v51, v68, 16, 1
	v_lshrrev_b32_e32 v17, 16, v17
	v_add3_u32 v51, v68, v51, s26
	v_and_or_b32 v51, v51, s27, v17
	v_or_b32_e32 v17, s18, v84
	v_lshlrev_b32_e32 v70, 9, v17
	v_mov_b32_e32 v71, v3
	v_lshl_add_u64 v[70:71], v[54:55], 0, v[70:71]
	v_bfe_u32 v17, v57, 16, 1
	global_store_dwordx4 v[70:71], v[48:51], off sc1
	v_add3_u32 v17, v57, v17, s26
	v_lshrrev_b32_e32 v17, 16, v17
	v_bfe_u32 v48, v53, 16, 1
	v_add3_u32 v48, v53, v48, s26
	v_and_or_b32 v48, v48, s27, v17
	v_bfe_u32 v17, v59, 16, 1
	v_add3_u32 v17, v59, v17, s26
	v_bfe_u32 v49, v61, 16, 1
	v_lshrrev_b32_e32 v17, 16, v17
	v_add3_u32 v49, v61, v49, s26
	v_and_or_b32 v49, v49, s27, v17
	v_bfe_u32 v17, v63, 16, 1
	v_add3_u32 v17, v63, v17, s26
	v_bfe_u32 v50, v65, 16, 1
	v_lshrrev_b32_e32 v17, 16, v17
	v_add3_u32 v50, v65, v50, s26
	v_and_or_b32 v50, v50, s27, v17
	v_bfe_u32 v17, v67, 16, 1
	v_add3_u32 v17, v67, v17, s26
	v_bfe_u32 v51, v69, 16, 1
	v_lshrrev_b32_e32 v17, 16, v17
	v_add3_u32 v51, v69, v51, s26
	v_and_or_b32 v51, v51, s27, v17
	v_or_b32_e32 v17, s18, v85
	v_lshlrev_b32_e32 v52, 9, v17
	v_mov_b32_e32 v53, v3
	v_lshl_add_u64 v[52:53], v[54:55], 0, v[52:53]
	global_store_dwordx4 v[52:53], v[48:51], off sc1
	s_waitcnt lgkmcnt(0)
	s_mov_b64 s[18:19], 0

.LBB0_346:
	v_lshl_add_u64 v[102:103], v[78:79], 0, s[18:19]
	v_lshl_add_u64 v[104:105], v[76:77], 0, s[18:19]
	v_lshl_add_u64 v[106:107], v[74:75], 0, s[18:19]
	v_lshl_add_u64 v[108:109], v[72:73], 0, s[18:19]
	v_lshl_add_u64 v[110:111], v[70:71], 0, s[18:19]
	v_lshl_add_u64 v[112:113], v[68:69], 0, s[18:19]
	v_lshl_add_u64 v[114:115], v[66:67], 0, s[18:19]
	v_lshl_add_u64 v[116:117], v[64:65], 0, s[18:19]
	v_lshl_add_u64 v[118:119], v[62:63], 0, s[18:19]
	v_lshl_add_u64 v[120:121], v[60:61], 0, s[18:19]
	v_lshl_add_u64 v[122:123], v[58:59], 0, s[18:19]
	v_lshl_add_u64 v[124:125], v[56:57], 0, s[18:19]
	v_lshl_add_u64 v[126:127], v[54:55], 0, s[18:19]
	v_lshl_add_u64 v[128:129], v[52:53], 0, s[18:19]
	v_lshl_add_u64 v[130:131], v[50:51], 0, s[18:19]
	v_lshl_add_u64 v[132:133], v[48:49], 0, s[18:19]
	global_load_dword v102, v[102:103], off nt
	s_nop 0
	global_load_dword v103, v[104:105], off nt
	s_nop 0
	global_load_dword v104, v[106:107], off nt
	global_load_dword v105, v[108:109], off nt
	s_nop 0
	global_load_dword v106, v[110:111], off nt
	global_load_dword v107, v[112:113], off nt
	global_load_dword v108, v[114:115], off nt
	global_load_dword v109, v[116:117], off nt
	s_nop 0
	global_load_dword v110, v[118:119], off nt
	global_load_dword v111, v[120:121], off nt
	global_load_dword v112, v[122:123], off nt
	global_load_dword v113, v[124:125], off nt
	global_load_dword v114, v[126:127], off nt
	global_load_dword v115, v[128:129], off nt
	global_load_dword v116, v[130:131], off nt
	global_load_dword v117, v[132:133], off nt
	s_add_u32 s18, s18, 0x20000
	s_addc_u32 s19, s19, 0
	v_add_u32_e32 v118, 0x400, v17
	v_add_u32_e32 v119, 0x800, v17
	v_add_u32_e32 v120, 0xc00, v17
	s_cmp_lg_u32 s18, 0x40000
	s_waitcnt vmcnt(14)
	ds_write2_b32 v17, v102, v103 offset1:66
	s_waitcnt vmcnt(12)
	ds_write2_b32 v17, v104, v105 offset0:132 offset1:198
	s_waitcnt vmcnt(10)
	ds_write2_b32 v118, v106, v107 offset0:8 offset1:74
	s_waitcnt vmcnt(8)
	ds_write2_b32 v118, v108, v109 offset0:140 offset1:206
	s_waitcnt vmcnt(6)
	ds_write2_b32 v119, v110, v111 offset0:16 offset1:82
	s_waitcnt vmcnt(4)
	ds_write2_b32 v119, v112, v113 offset0:148 offset1:214
	s_waitcnt vmcnt(2)
	ds_write2_b32 v120, v114, v115 offset0:24 offset1:90
	s_waitcnt vmcnt(0)
	ds_write2_b32 v120, v116, v117 offset0:156 offset1:222
	v_add_u32_e32 v17, 0x1080, v17
	s_cbranch_scc1 .LBB0_346
	s_waitcnt lgkmcnt(0)
	ds_read2_b32 v[52:53], v82 offset1:8
	ds_read2_b32 v[56:57], v82 offset0:33 offset1:41
	ds_read2_b32 v[58:59], v82 offset0:66 offset1:74
	ds_read2_b32 v[60:61], v82 offset0:99 offset1:107
	ds_read2_b32 v[62:63], v82 offset0:132 offset1:140
	s_waitcnt lgkmcnt(4)
	v_bfe_u32 v17, v52, 16, 1
	v_add3_u32 v17, v52, v17, s26
	s_waitcnt lgkmcnt(3)
	v_bfe_u32 v48, v56, 16, 1
	v_lshrrev_b32_e32 v17, 16, v17
	v_add3_u32 v48, v56, v48, s26
	ds_read2_b32 v[64:65], v82 offset0:165 offset1:173
	v_and_or_b32 v48, v48, s27, v17
	s_waitcnt lgkmcnt(3)
	v_bfe_u32 v17, v58, 16, 1
	v_add3_u32 v17, v58, v17, s26
	s_waitcnt lgkmcnt(2)
	v_bfe_u32 v49, v60, 16, 1
	ds_read2_b32 v[66:67], v82 offset0:198 offset1:206
	v_lshrrev_b32_e32 v17, 16, v17
	v_add3_u32 v49, v60, v49, s26
	ds_read2_b32 v[68:69], v82 offset0:231 offset1:239
	v_and_or_b32 v49, v49, s27, v17
	s_waitcnt lgkmcnt(3)
	v_bfe_u32 v17, v62, 16, 1
	v_add3_u32 v17, v62, v17, s26
	s_waitcnt lgkmcnt(2)
	v_bfe_u32 v50, v64, 16, 1
	v_lshrrev_b32_e32 v17, 16, v17
	v_add3_u32 v50, v64, v50, s26
	v_and_or_b32 v50, v50, s27, v17
	s_waitcnt lgkmcnt(1)
	v_bfe_u32 v17, v66, 16, 1
	s_add_i32 s21, s21, 0x1f800
	s_lshl_b32 s18, s28, 5
	v_add3_u32 v17, v66, v17, s26
	s_waitcnt lgkmcnt(0)
	v_bfe_u32 v51, v68, 16, 1
	s_and_b32 s16, s21, 0x1ffc0
	s_and_b32 s18, s18, 0x3e0
	v_lshrrev_b32_e32 v17, 16, v17
	v_add3_u32 v51, v68, v51, s26
	s_lshl_b32 s16, s16, 1
	v_and_or_b32 v51, v51, s27, v17
	v_or_b32_e32 v17, s18, v81
	v_lshl_add_u64 v[54:55], v[6:7], 0, s[16:17]
	v_lshlrev_b32_e32 v70, 11, v17
	v_mov_b32_e32 v71, v3
	v_lshl_add_u64 v[70:71], v[54:55], 0, v[70:71]
	v_bfe_u32 v17, v53, 16, 1
	global_store_dwordx4 v[70:71], v[48:51], off sc1
	v_add3_u32 v17, v53, v17, s26
	v_lshrrev_b32_e32 v17, 16, v17
	v_bfe_u32 v48, v57, 16, 1
	v_add3_u32 v48, v57, v48, s26
	v_and_or_b32 v48, v48, s27, v17
	v_bfe_u32 v17, v59, 16, 1
	v_add3_u32 v17, v59, v17, s26
	v_bfe_u32 v49, v61, 16, 1
	v_lshrrev_b32_e32 v17, 16, v17
	v_add3_u32 v49, v61, v49, s26
	v_and_or_b32 v49, v49, s27, v17
	v_bfe_u32 v17, v63, 16, 1
	v_add3_u32 v17, v63, v17, s26
	v_bfe_u32 v50, v65, 16, 1
	v_lshrrev_b32_e32 v17, 16, v17
	v_add3_u32 v50, v65, v50, s26
	v_and_or_b32 v50, v50, s27, v17
	v_bfe_u32 v17, v67, 16, 1
	v_add3_u32 v17, v67, v17, s26
	v_bfe_u32 v51, v69, 16, 1
	v_lshrrev_b32_e32 v17, 16, v17
	v_add3_u32 v51, v69, v51, s26
	v_and_or_b32 v51, v51, s27, v17
	v_or_b32_e32 v17, s18, v83
	v_lshlrev_b32_e32 v52, 11, v17
	v_mov_b32_e32 v53, v3
	ds_read2_b32 v[56:57], v82 offset0:16 offset1:24
	v_lshl_add_u64 v[52:53], v[54:55], 0, v[52:53]
	global_store_dwordx4 v[52:53], v[48:51], off sc1
	ds_read2_b32 v[52:53], v82 offset0:49 offset1:57
	ds_read2_b32 v[58:59], v82 offset0:82 offset1:90
	ds_read2_b32 v[60:61], v82 offset0:115 offset1:123
	s_waitcnt lgkmcnt(3)
	v_bfe_u32 v17, v56, 16, 1
	v_add3_u32 v17, v56, v17, s26
	s_waitcnt lgkmcnt(2)
	v_bfe_u32 v48, v52, 16, 1
	ds_read2_b32 v[62:63], v82 offset0:148 offset1:156
	v_lshrrev_b32_e32 v17, 16, v17
	v_add3_u32 v48, v52, v48, s26
	ds_read2_b32 v[64:65], v82 offset0:181 offset1:189
	v_and_or_b32 v48, v48, s27, v17
	s_waitcnt lgkmcnt(3)
	v_bfe_u32 v17, v58, 16, 1
	v_add3_u32 v17, v58, v17, s26
	s_waitcnt lgkmcnt(2)
	v_bfe_u32 v49, v60, 16, 1
	ds_read2_b32 v[66:67], v82 offset0:214 offset1:222
	v_lshrrev_b32_e32 v17, 16, v17
	v_add3_u32 v49, v60, v49, s26
	ds_read2_b32 v[68:69], v82 offset0:247 offset1:255
	v_and_or_b32 v49, v49, s27, v17
	s_waitcnt lgkmcnt(3)
	v_bfe_u32 v17, v62, 16, 1
	v_add3_u32 v17, v62, v17, s26
	s_waitcnt lgkmcnt(2)
	v_bfe_u32 v50, v64, 16, 1
	v_lshrrev_b32_e32 v17, 16, v17
	v_add3_u32 v50, v64, v50, s26
	v_and_or_b32 v50, v50, s27, v17
	s_waitcnt lgkmcnt(1)
	v_bfe_u32 v17, v66, 16, 1
	v_add3_u32 v17, v66, v17, s26
	s_waitcnt lgkmcnt(0)
	v_bfe_u32 v51, v68, 16, 1
	v_lshrrev_b32_e32 v17, 16, v17
	v_add3_u32 v51, v68, v51, s26
	v_and_or_b32 v51, v51, s27, v17
	v_or_b32_e32 v17, s18, v84
	v_lshlrev_b32_e32 v70, 11, v17
	v_mov_b32_e32 v71, v3
	v_lshl_add_u64 v[70:71], v[54:55], 0, v[70:71]
	v_bfe_u32 v17, v57, 16, 1
	global_store_dwordx4 v[70:71], v[48:51], off sc1
	v_add3_u32 v17, v57, v17, s26
	v_lshrrev_b32_e32 v17, 16, v17
	v_bfe_u32 v48, v53, 16, 1
	v_add3_u32 v48, v53, v48, s26
	v_and_or_b32 v48, v48, s27, v17
	v_bfe_u32 v17, v59, 16, 1
	v_add3_u32 v17, v59, v17, s26
	v_bfe_u32 v49, v61, 16, 1
	v_lshrrev_b32_e32 v17, 16, v17
	v_add3_u32 v49, v61, v49, s26
	v_and_or_b32 v49, v49, s27, v17
	v_bfe_u32 v17, v63, 16, 1
	v_add3_u32 v17, v63, v17, s26
	v_bfe_u32 v50, v65, 16, 1
	v_lshrrev_b32_e32 v17, 16, v17
	v_add3_u32 v50, v65, v50, s26
	v_and_or_b32 v50, v50, s27, v17
	v_bfe_u32 v17, v67, 16, 1
	v_add3_u32 v17, v67, v17, s26
	v_bfe_u32 v51, v69, 16, 1
	v_lshrrev_b32_e32 v17, 16, v17
	v_add3_u32 v51, v69, v51, s26
	v_and_or_b32 v51, v51, s27, v17
	v_or_b32_e32 v17, s18, v85
	v_lshlrev_b32_e32 v52, 11, v17
	v_mov_b32_e32 v53, v3
	v_lshl_add_u64 v[52:53], v[54:55], 0, v[52:53]
	global_store_dwordx4 v[52:53], v[48:51], off sc1
	s_waitcnt lgkmcnt(0)

.LBB0_351:
	v_lshl_add_u64 v[102:103], v[78:79], 0, s[18:19]
	v_lshl_add_u64 v[104:105], v[76:77], 0, s[18:19]
	v_lshl_add_u64 v[106:107], v[74:75], 0, s[18:19]
	v_lshl_add_u64 v[108:109], v[72:73], 0, s[18:19]
	v_lshl_add_u64 v[110:111], v[70:71], 0, s[18:19]
	v_lshl_add_u64 v[112:113], v[68:69], 0, s[18:19]
	v_lshl_add_u64 v[114:115], v[66:67], 0, s[18:19]
	v_lshl_add_u64 v[116:117], v[64:65], 0, s[18:19]
	v_lshl_add_u64 v[118:119], v[62:63], 0, s[18:19]
	v_lshl_add_u64 v[120:121], v[60:61], 0, s[18:19]
	v_lshl_add_u64 v[122:123], v[58:59], 0, s[18:19]
	v_lshl_add_u64 v[124:125], v[56:57], 0, s[18:19]
	v_lshl_add_u64 v[126:127], v[54:55], 0, s[18:19]
	v_lshl_add_u64 v[128:129], v[52:53], 0, s[18:19]
	v_lshl_add_u64 v[130:131], v[50:51], 0, s[18:19]
	v_lshl_add_u64 v[132:133], v[48:49], 0, s[18:19]
	global_load_dword v102, v[102:103], off nt
	s_nop 0
	global_load_dword v103, v[104:105], off nt
	s_nop 0
	global_load_dword v104, v[106:107], off nt
	global_load_dword v105, v[108:109], off nt
	s_nop 0
	global_load_dword v106, v[110:111], off nt
	global_load_dword v107, v[112:113], off nt
	global_load_dword v108, v[114:115], off nt
	global_load_dword v109, v[116:117], off nt
	s_nop 0
	global_load_dword v110, v[118:119], off nt
	global_load_dword v111, v[120:121], off nt
	global_load_dword v112, v[122:123], off nt
	global_load_dword v113, v[124:125], off nt
	global_load_dword v114, v[126:127], off nt
	global_load_dword v115, v[128:129], off nt
	global_load_dword v116, v[130:131], off nt
	global_load_dword v117, v[132:133], off nt
	s_add_u32 s18, s18, 0x20000
	s_addc_u32 s19, s19, 0
	v_add_u32_e32 v118, 0x400, v17
	v_add_u32_e32 v119, 0x800, v17
	v_add_u32_e32 v120, 0xc00, v17
	s_cmp_lg_u32 s18, 0x40000
	s_waitcnt vmcnt(14)
	ds_write2_b32 v17, v102, v103 offset1:66
	s_waitcnt vmcnt(12)
	ds_write2_b32 v17, v104, v105 offset0:132 offset1:198
	s_waitcnt vmcnt(10)
	ds_write2_b32 v118, v106, v107 offset0:8 offset1:74
	s_waitcnt vmcnt(8)
	ds_write2_b32 v118, v108, v109 offset0:140 offset1:206
	s_waitcnt vmcnt(6)
	ds_write2_b32 v119, v110, v111 offset0:16 offset1:82
	s_waitcnt vmcnt(4)
	ds_write2_b32 v119, v112, v113 offset0:148 offset1:214
	s_waitcnt vmcnt(2)
	ds_write2_b32 v120, v114, v115 offset0:24 offset1:90
	s_waitcnt vmcnt(0)
	ds_write2_b32 v120, v116, v117 offset0:156 offset1:222
	v_add_u32_e32 v17, 0x1080, v17
	s_cbranch_scc1 .LBB0_351
	s_waitcnt lgkmcnt(0)
	ds_read2_b32 v[52:53], v82 offset1:8
	ds_read2_b32 v[56:57], v82 offset0:33 offset1:41
	ds_read2_b32 v[58:59], v82 offset0:66 offset1:74
	ds_read2_b32 v[60:61], v82 offset0:99 offset1:107
	ds_read2_b32 v[62:63], v82 offset0:132 offset1:140
	s_waitcnt lgkmcnt(4)
	v_bfe_u32 v17, v52, 16, 1
	v_add3_u32 v17, v52, v17, s26
	s_waitcnt lgkmcnt(3)
	v_bfe_u32 v48, v56, 16, 1
	v_lshrrev_b32_e32 v17, 16, v17
	v_add3_u32 v48, v56, v48, s26
	ds_read2_b32 v[64:65], v82 offset0:165 offset1:173
	v_and_or_b32 v48, v48, s27, v17
	s_waitcnt lgkmcnt(3)
	v_bfe_u32 v17, v58, 16, 1
	v_add3_u32 v17, v58, v17, s26
	s_waitcnt lgkmcnt(2)
	v_bfe_u32 v49, v60, 16, 1
	ds_read2_b32 v[66:67], v82 offset0:198 offset1:206
	v_lshrrev_b32_e32 v17, 16, v17
	v_add3_u32 v49, v60, v49, s26
	ds_read2_b32 v[68:69], v82 offset0:231 offset1:239
	v_and_or_b32 v49, v49, s27, v17
	s_waitcnt lgkmcnt(3)
	v_bfe_u32 v17, v62, 16, 1
	v_add3_u32 v17, v62, v17, s26
	s_waitcnt lgkmcnt(2)
	v_bfe_u32 v50, v64, 16, 1
	v_lshrrev_b32_e32 v17, 16, v17
	v_add3_u32 v50, v64, v50, s26
	s_lshl_b32 s16, s28, 1
	v_and_or_b32 v50, v50, s27, v17
	s_waitcnt lgkmcnt(1)
	v_bfe_u32 v17, v66, 16, 1
	s_add_i32 s16, s16, 0x1fc00
	s_lshl_b32 s18, s28, 5
	v_add3_u32 v17, v66, v17, s26
	s_waitcnt lgkmcnt(0)
	v_bfe_u32 v51, v68, 16, 1
	s_and_b32 s16, s16, 0x1ffc0
	s_and_b32 s18, s18, 0x3e0
	v_lshrrev_b32_e32 v17, 16, v17
	v_add3_u32 v51, v68, v51, s26
	s_lshl_b32 s16, s16, 1
	v_and_or_b32 v51, v51, s27, v17
	v_or_b32_e32 v17, s18, v81
	v_lshl_add_u64 v[54:55], v[8:9], 0, s[16:17]
	v_lshlrev_b32_e32 v70, 11, v17
	v_mov_b32_e32 v71, v3
	v_lshl_add_u64 v[70:71], v[54:55], 0, v[70:71]
	v_bfe_u32 v17, v53, 16, 1
	global_store_dwordx4 v[70:71], v[48:51], off sc1
	v_add3_u32 v17, v53, v17, s26
	v_lshrrev_b32_e32 v17, 16, v17
	v_bfe_u32 v48, v57, 16, 1
	v_add3_u32 v48, v57, v48, s26
	v_and_or_b32 v48, v48, s27, v17
	v_bfe_u32 v17, v59, 16, 1
	v_add3_u32 v17, v59, v17, s26
	v_bfe_u32 v49, v61, 16, 1
	v_lshrrev_b32_e32 v17, 16, v17
	v_add3_u32 v49, v61, v49, s26
	v_and_or_b32 v49, v49, s27, v17
	v_bfe_u32 v17, v63, 16, 1
	v_add3_u32 v17, v63, v17, s26
	v_bfe_u32 v50, v65, 16, 1
	v_lshrrev_b32_e32 v17, 16, v17
	v_add3_u32 v50, v65, v50, s26
	v_and_or_b32 v50, v50, s27, v17
	v_bfe_u32 v17, v67, 16, 1
	v_add3_u32 v17, v67, v17, s26
	v_bfe_u32 v51, v69, 16, 1
	v_lshrrev_b32_e32 v17, 16, v17
	v_add3_u32 v51, v69, v51, s26
	v_and_or_b32 v51, v51, s27, v17
	v_or_b32_e32 v17, s18, v83
	v_lshlrev_b32_e32 v52, 11, v17
	v_mov_b32_e32 v53, v3
	ds_read2_b32 v[56:57], v82 offset0:16 offset1:24
	v_lshl_add_u64 v[52:53], v[54:55], 0, v[52:53]
	global_store_dwordx4 v[52:53], v[48:51], off sc1
	ds_read2_b32 v[52:53], v82 offset0:49 offset1:57
	ds_read2_b32 v[58:59], v82 offset0:82 offset1:90
	ds_read2_b32 v[60:61], v82 offset0:115 offset1:123
	s_waitcnt lgkmcnt(3)
	v_bfe_u32 v17, v56, 16, 1
	v_add3_u32 v17, v56, v17, s26
	s_waitcnt lgkmcnt(2)
	v_bfe_u32 v48, v52, 16, 1
	ds_read2_b32 v[62:63], v82 offset0:148 offset1:156
	v_lshrrev_b32_e32 v17, 16, v17
	v_add3_u32 v48, v52, v48, s26
	ds_read2_b32 v[64:65], v82 offset0:181 offset1:189
	v_and_or_b32 v48, v48, s27, v17
	s_waitcnt lgkmcnt(3)
	v_bfe_u32 v17, v58, 16, 1
	v_add3_u32 v17, v58, v17, s26
	s_waitcnt lgkmcnt(2)
	v_bfe_u32 v49, v60, 16, 1
	ds_read2_b32 v[66:67], v82 offset0:214 offset1:222
	v_lshrrev_b32_e32 v17, 16, v17
	v_add3_u32 v49, v60, v49, s26
	ds_read2_b32 v[68:69], v82 offset0:247 offset1:255
	v_and_or_b32 v49, v49, s27, v17
	s_waitcnt lgkmcnt(3)
	v_bfe_u32 v17, v62, 16, 1
	v_add3_u32 v17, v62, v17, s26
	s_waitcnt lgkmcnt(2)
	v_bfe_u32 v50, v64, 16, 1
	v_lshrrev_b32_e32 v17, 16, v17
	v_add3_u32 v50, v64, v50, s26
	v_and_or_b32 v50, v50, s27, v17
	s_waitcnt lgkmcnt(1)
	v_bfe_u32 v17, v66, 16, 1
	v_add3_u32 v17, v66, v17, s26
	s_waitcnt lgkmcnt(0)
	v_bfe_u32 v51, v68, 16, 1
	v_lshrrev_b32_e32 v17, 16, v17
	v_add3_u32 v51, v68, v51, s26
	v_and_or_b32 v51, v51, s27, v17
	v_or_b32_e32 v17, s18, v84
	v_lshlrev_b32_e32 v70, 11, v17
	v_mov_b32_e32 v71, v3
	v_lshl_add_u64 v[70:71], v[54:55], 0, v[70:71]
	v_bfe_u32 v17, v57, 16, 1
	global_store_dwordx4 v[70:71], v[48:51], off sc1
	v_add3_u32 v17, v57, v17, s26
	v_lshrrev_b32_e32 v17, 16, v17
	v_bfe_u32 v48, v53, 16, 1
	v_add3_u32 v48, v53, v48, s26
	v_and_or_b32 v48, v48, s27, v17
	v_bfe_u32 v17, v59, 16, 1
	v_add3_u32 v17, v59, v17, s26
	v_bfe_u32 v49, v61, 16, 1
	v_lshrrev_b32_e32 v17, 16, v17
	v_add3_u32 v49, v61, v49, s26
	v_and_or_b32 v49, v49, s27, v17
	v_bfe_u32 v17, v63, 16, 1
	v_add3_u32 v17, v63, v17, s26
	v_bfe_u32 v50, v65, 16, 1
	v_lshrrev_b32_e32 v17, 16, v17
	v_add3_u32 v50, v65, v50, s26
	v_and_or_b32 v50, v50, s27, v17
	v_bfe_u32 v17, v67, 16, 1
	v_add3_u32 v17, v67, v17, s26
	v_bfe_u32 v51, v69, 16, 1
	v_lshrrev_b32_e32 v17, 16, v17
	v_add3_u32 v51, v69, v51, s26
	v_and_or_b32 v51, v51, s27, v17
	v_or_b32_e32 v17, s18, v85
	v_lshlrev_b32_e32 v52, 11, v17
	v_mov_b32_e32 v53, v3
	v_lshl_add_u64 v[52:53], v[54:55], 0, v[52:53]
	global_store_dwordx4 v[52:53], v[48:51], off sc1
	s_waitcnt lgkmcnt(0)

.LBB0_356:
	v_lshl_add_u64 v[50:51], v[46:47], 0, s[18:19]
	v_lshl_add_u64 v[52:53], v[44:45], 0, s[18:19]
	v_lshl_add_u64 v[54:55], v[42:43], 0, s[18:19]
	v_lshl_add_u64 v[56:57], v[40:41], 0, s[18:19]
	v_lshl_add_u64 v[58:59], v[38:39], 0, s[18:19]
	v_lshl_add_u64 v[60:61], v[36:37], 0, s[18:19]
	v_lshl_add_u64 v[62:63], v[34:35], 0, s[18:19]
	v_lshl_add_u64 v[64:65], v[32:33], 0, s[18:19]
	v_lshl_add_u64 v[66:67], v[30:31], 0, s[18:19]
	v_lshl_add_u64 v[68:69], v[28:29], 0, s[18:19]
	v_lshl_add_u64 v[70:71], v[26:27], 0, s[18:19]
	v_lshl_add_u64 v[72:73], v[24:25], 0, s[18:19]
	v_lshl_add_u64 v[74:75], v[22:23], 0, s[18:19]
	v_lshl_add_u64 v[76:77], v[20:21], 0, s[18:19]
	v_lshl_add_u64 v[78:79], v[18:19], 0, s[18:19]
	v_lshl_add_u64 v[102:103], v[48:49], 0, s[18:19]
	global_load_dword v17, v[50:51], off nt
	global_load_dword v104, v[52:53], off nt
	global_load_dword v105, v[54:55], off nt
	global_load_dword v106, v[56:57], off nt
	global_load_dword v107, v[58:59], off nt
	global_load_dword v108, v[60:61], off nt
	global_load_dword v109, v[62:63], off nt
	global_load_dword v110, v[64:65], off nt
	global_load_dword v111, v[66:67], off nt
	global_load_dword v112, v[68:69], off nt
	global_load_dword v113, v[70:71], off nt
	global_load_dword v114, v[72:73], off nt
	global_load_dword v115, v[74:75], off nt
	global_load_dword v116, v[76:77], off nt
	global_load_dword v117, v[78:79], off nt
	global_load_dword v50, v[102:103], off nt
	s_add_u32 s18, s18, 0x20000
	s_addc_u32 s19, s19, 0
	v_add_u32_e32 v51, 0x400, v2
	v_add_u32_e32 v52, 0x800, v2
	v_add_u32_e32 v53, 0xc00, v2
	s_cmp_lg_u32 s18, 0x40000
	s_waitcnt vmcnt(14)
	ds_write2_b32 v2, v17, v104 offset1:66
	s_waitcnt vmcnt(12)
	ds_write2_b32 v2, v105, v106 offset0:132 offset1:198
	s_waitcnt vmcnt(10)
	ds_write2_b32 v51, v107, v108 offset0:8 offset1:74
	s_waitcnt vmcnt(8)
	ds_write2_b32 v51, v109, v110 offset0:140 offset1:206
	s_waitcnt vmcnt(6)
	ds_write2_b32 v52, v111, v112 offset0:16 offset1:82
	s_waitcnt vmcnt(4)
	ds_write2_b32 v52, v113, v114 offset0:148 offset1:214
	s_waitcnt vmcnt(2)
	ds_write2_b32 v53, v115, v116 offset0:24 offset1:90
	s_waitcnt vmcnt(0)
	ds_write2_b32 v53, v117, v50 offset0:156 offset1:222
	v_add_u32_e32 v2, 0x1080, v2
	s_cbranch_scc1 .LBB0_356
	s_waitcnt lgkmcnt(0)
	ds_read2_b32 v[22:23], v82 offset1:8
	ds_read2_b32 v[26:27], v82 offset0:33 offset1:41
	ds_read2_b32 v[28:29], v82 offset0:66 offset1:74
	ds_read2_b32 v[30:31], v82 offset0:99 offset1:107
	ds_read2_b32 v[32:33], v82 offset0:132 offset1:140
	s_waitcnt lgkmcnt(4)
	v_bfe_u32 v2, v22, 16, 1
	v_add3_u32 v2, v22, v2, s26
	s_waitcnt lgkmcnt(3)
	v_bfe_u32 v17, v26, 16, 1
	v_lshrrev_b32_e32 v2, 16, v2
	v_add3_u32 v17, v26, v17, s26
	ds_read2_b32 v[34:35], v82 offset0:165 offset1:173
	v_and_or_b32 v18, v17, s27, v2
	s_waitcnt lgkmcnt(3)
	v_bfe_u32 v2, v28, 16, 1
	v_add3_u32 v2, v28, v2, s26
	s_waitcnt lgkmcnt(2)
	v_bfe_u32 v17, v30, 16, 1
	ds_read2_b32 v[36:37], v82 offset0:198 offset1:206
	v_lshrrev_b32_e32 v2, 16, v2
	v_add3_u32 v17, v30, v17, s26
	ds_read2_b32 v[38:39], v82 offset0:231 offset1:239
	v_and_or_b32 v19, v17, s27, v2
	s_waitcnt lgkmcnt(3)
	v_bfe_u32 v2, v32, 16, 1
	v_add3_u32 v2, v32, v2, s26
	s_waitcnt lgkmcnt(2)
	v_bfe_u32 v17, v34, 16, 1
	v_lshrrev_b32_e32 v2, 16, v2
	v_add3_u32 v17, v34, v17, s26
	v_and_or_b32 v20, v17, s27, v2
	s_waitcnt lgkmcnt(1)
	v_bfe_u32 v2, v36, 16, 1
	s_lshl_b32 s16, s28, 5
	v_add3_u32 v2, v36, v2, s26
	s_waitcnt lgkmcnt(0)
	v_bfe_u32 v17, v38, 16, 1
	s_and_b32 s18, s16, 0x3e0
	s_lshl_b32 s16, s28, 2
	v_lshrrev_b32_e32 v2, 16, v2
	v_add3_u32 v17, v38, v17, s26
	s_and_b32 s16, s16, 0x380
	v_and_or_b32 v21, v17, s27, v2
	v_or_b32_e32 v2, s18, v81
	v_lshl_add_u64 v[24:25], v[10:11], 0, s[16:17]
	v_lshlrev_b32_e32 v2, 10, v2
	v_lshl_add_u64 v[40:41], v[24:25], 0, v[2:3]
	v_bfe_u32 v2, v23, 16, 1
	v_add3_u32 v2, v23, v2, s26
	v_bfe_u32 v17, v27, 16, 1
	v_lshrrev_b32_e32 v2, 16, v2
	v_add3_u32 v17, v27, v17, s26
	global_store_dwordx4 v[40:41], v[18:21], off sc1
	ds_read2_b32 v[22:23], v82 offset0:16 offset1:24
	s_nop 0
	v_and_or_b32 v18, v17, s27, v2
	v_bfe_u32 v2, v29, 16, 1
	v_add3_u32 v2, v29, v2, s26
	v_bfe_u32 v17, v31, 16, 1
	v_lshrrev_b32_e32 v2, 16, v2
	v_add3_u32 v17, v31, v17, s26
	v_and_or_b32 v19, v17, s27, v2
	v_bfe_u32 v2, v33, 16, 1
	v_add3_u32 v2, v33, v2, s26
	v_bfe_u32 v17, v35, 16, 1
	v_lshrrev_b32_e32 v2, 16, v2
	v_add3_u32 v17, v35, v17, s26
	v_and_or_b32 v20, v17, s27, v2
	v_bfe_u32 v2, v37, 16, 1
	v_add3_u32 v2, v37, v2, s26
	v_bfe_u32 v17, v39, 16, 1
	v_lshrrev_b32_e32 v2, 16, v2
	v_add3_u32 v17, v39, v17, s26
	v_and_or_b32 v21, v17, s27, v2
	v_or_b32_e32 v2, s18, v83
	v_lshlrev_b32_e32 v2, 10, v2
	v_lshl_add_u64 v[26:27], v[24:25], 0, v[2:3]
	global_store_dwordx4 v[26:27], v[18:21], off sc1
	ds_read2_b32 v[26:27], v82 offset0:49 offset1:57
	ds_read2_b32 v[28:29], v82 offset0:82 offset1:90
	ds_read2_b32 v[30:31], v82 offset0:115 offset1:123
	s_waitcnt lgkmcnt(3)
	v_bfe_u32 v2, v22, 16, 1
	v_add3_u32 v2, v22, v2, s26
	s_waitcnt lgkmcnt(2)
	v_bfe_u32 v17, v26, 16, 1
	ds_read2_b32 v[32:33], v82 offset0:148 offset1:156
	v_lshrrev_b32_e32 v2, 16, v2
	v_add3_u32 v17, v26, v17, s26
	ds_read2_b32 v[34:35], v82 offset0:181 offset1:189
	v_and_or_b32 v18, v17, s27, v2
	s_waitcnt lgkmcnt(3)
	v_bfe_u32 v2, v28, 16, 1
	v_add3_u32 v2, v28, v2, s26
	s_waitcnt lgkmcnt(2)
	v_bfe_u32 v17, v30, 16, 1
	ds_read2_b32 v[36:37], v82 offset0:214 offset1:222
	v_lshrrev_b32_e32 v2, 16, v2
	v_add3_u32 v17, v30, v17, s26
	ds_read2_b32 v[38:39], v82 offset0:247 offset1:255
	v_and_or_b32 v19, v17, s27, v2
	s_waitcnt lgkmcnt(3)
	v_bfe_u32 v2, v32, 16, 1
	v_add3_u32 v2, v32, v2, s26
	s_waitcnt lgkmcnt(2)
	v_bfe_u32 v17, v34, 16, 1
	v_lshrrev_b32_e32 v2, 16, v2
	v_add3_u32 v17, v34, v17, s26
	v_and_or_b32 v20, v17, s27, v2
	s_waitcnt lgkmcnt(1)
	v_bfe_u32 v2, v36, 16, 1
	v_add3_u32 v2, v36, v2, s26
	s_waitcnt lgkmcnt(0)
	v_bfe_u32 v17, v38, 16, 1
	v_lshrrev_b32_e32 v2, 16, v2
	v_add3_u32 v17, v38, v17, s26
	v_and_or_b32 v21, v17, s27, v2
	v_or_b32_e32 v2, s18, v84
	v_lshlrev_b32_e32 v2, 10, v2
	v_lshl_add_u64 v[40:41], v[24:25], 0, v[2:3]
	v_bfe_u32 v2, v23, 16, 1
	v_add3_u32 v2, v23, v2, s26
	v_bfe_u32 v17, v27, 16, 1
	v_lshrrev_b32_e32 v2, 16, v2
	v_add3_u32 v17, v27, v17, s26
	global_store_dwordx4 v[40:41], v[18:21], off sc1
	s_nop 1
	v_and_or_b32 v18, v17, s27, v2
	v_bfe_u32 v2, v29, 16, 1
	v_add3_u32 v2, v29, v2, s26
	v_bfe_u32 v17, v31, 16, 1
	v_lshrrev_b32_e32 v2, 16, v2
	v_add3_u32 v17, v31, v17, s26
	v_and_or_b32 v19, v17, s27, v2
	v_bfe_u32 v2, v33, 16, 1
	v_add3_u32 v2, v33, v2, s26
	v_bfe_u32 v17, v35, 16, 1
	v_lshrrev_b32_e32 v2, 16, v2
	v_add3_u32 v17, v35, v17, s26
	v_and_or_b32 v20, v17, s27, v2
	v_bfe_u32 v2, v37, 16, 1
	v_add3_u32 v2, v37, v2, s26
	v_bfe_u32 v17, v39, 16, 1
	v_lshrrev_b32_e32 v2, 16, v2
	v_add3_u32 v17, v39, v17, s26
	v_and_or_b32 v21, v17, s27, v2
	v_or_b32_e32 v2, s18, v85
	v_lshlrev_b32_e32 v2, 10, v2
	v_lshl_add_u64 v[22:23], v[24:25], 0, v[2:3]
	global_store_dwordx4 v[22:23], v[18:21], off sc1
	s_waitcnt lgkmcnt(0)

.LBB0_361:
	v_add_u32_e32 v20, s16, v2
	v_ashrrev_i32_e32 v21, 31, v20
	v_add_u32_e32 v22, 2, v20
	v_add_u32_e32 v24, 4, v20
	v_add_u32_e32 v26, 6, v20
	v_add_u32_e32 v28, 8, v20
	v_add_u32_e32 v30, 10, v20
	v_add_u32_e32 v32, 12, v20
	v_add_u32_e32 v34, 14, v20
	v_add_u32_e32 v36, 16, v20
	v_add_u32_e32 v38, 18, v20
	v_add_u32_e32 v40, 20, v20
	v_add_u32_e32 v42, 22, v20
	v_add_u32_e32 v44, 24, v20
	v_add_u32_e32 v46, 26, v20
	v_add_u32_e32 v48, 28, v20
	v_add_u32_e32 v50, 30, v20
	v_lshlrev_b64 v[20:21], 12, v[20:21]
	v_ashrrev_i32_e32 v23, 31, v22
	v_ashrrev_i32_e32 v25, 31, v24
	v_ashrrev_i32_e32 v27, 31, v26
	v_ashrrev_i32_e32 v29, 31, v28
	v_ashrrev_i32_e32 v31, 31, v30
	v_ashrrev_i32_e32 v33, 31, v32
	v_ashrrev_i32_e32 v35, 31, v34
	v_ashrrev_i32_e32 v37, 31, v36
	v_ashrrev_i32_e32 v39, 31, v38
	v_ashrrev_i32_e32 v41, 31, v40
	v_ashrrev_i32_e32 v43, 31, v42
	v_ashrrev_i32_e32 v45, 31, v44
	v_ashrrev_i32_e32 v47, 31, v46
	v_ashrrev_i32_e32 v49, 31, v48
	v_ashrrev_i32_e32 v51, 31, v50
	v_lshl_add_u64 v[20:21], v[18:19], 0, v[20:21]
	v_lshlrev_b64 v[22:23], 12, v[22:23]
	v_lshlrev_b64 v[24:25], 12, v[24:25]
	v_lshlrev_b64 v[26:27], 12, v[26:27]
	v_lshlrev_b64 v[28:29], 12, v[28:29]
	v_lshlrev_b64 v[30:31], 12, v[30:31]
	v_lshlrev_b64 v[32:33], 12, v[32:33]
	v_lshlrev_b64 v[34:35], 12, v[34:35]
	v_lshlrev_b64 v[36:37], 12, v[36:37]
	v_lshlrev_b64 v[38:39], 12, v[38:39]
	v_lshlrev_b64 v[40:41], 12, v[40:41]
	v_lshlrev_b64 v[42:43], 12, v[42:43]
	v_lshlrev_b64 v[44:45], 12, v[44:45]
	v_lshlrev_b64 v[46:47], 12, v[46:47]
	v_lshlrev_b64 v[48:49], 12, v[48:49]
	v_lshlrev_b64 v[50:51], 12, v[50:51]
	v_lshl_add_u64 v[22:23], v[18:19], 0, v[22:23]
	v_lshl_add_u64 v[24:25], v[18:19], 0, v[24:25]
	v_lshl_add_u64 v[26:27], v[18:19], 0, v[26:27]
	v_lshl_add_u64 v[28:29], v[18:19], 0, v[28:29]
	v_lshl_add_u64 v[30:31], v[18:19], 0, v[30:31]
	v_lshl_add_u64 v[32:33], v[18:19], 0, v[32:33]
	v_lshl_add_u64 v[34:35], v[18:19], 0, v[34:35]
	v_lshl_add_u64 v[36:37], v[18:19], 0, v[36:37]
	v_lshl_add_u64 v[38:39], v[18:19], 0, v[38:39]
	v_lshl_add_u64 v[40:41], v[18:19], 0, v[40:41]
	v_lshl_add_u64 v[42:43], v[18:19], 0, v[42:43]
	v_lshl_add_u64 v[44:45], v[18:19], 0, v[44:45]
	v_lshl_add_u64 v[46:47], v[18:19], 0, v[46:47]
	v_lshl_add_u64 v[48:49], v[18:19], 0, v[48:49]
	v_lshl_add_u64 v[50:51], v[18:19], 0, v[50:51]
	global_load_dword v52, v[20:21], off nt
	global_load_dword v53, v[22:23], off nt
	global_load_dword v54, v[24:25], off nt
	global_load_dword v55, v[26:27], off nt
	global_load_dword v56, v[28:29], off nt
	global_load_dword v57, v[30:31], off nt
	global_load_dword v58, v[32:33], off nt
	global_load_dword v59, v[34:35], off nt
	global_load_dword v60, v[36:37], off nt
	global_load_dword v61, v[38:39], off nt
	global_load_dword v62, v[40:41], off nt
	global_load_dword v63, v[42:43], off nt
	global_load_dword v64, v[44:45], off nt
	global_load_dword v65, v[46:47], off nt
	global_load_dword v66, v[48:49], off nt
	global_load_dword v20, v[50:51], off nt
	s_add_i32 s16, s16, 32
	v_add_u32_e32 v21, 0x400, v17
	v_add_u32_e32 v22, 0x800, v17
	v_add_u32_e32 v23, 0xc00, v17
	s_cmp_lg_u32 s16, 64
	s_waitcnt vmcnt(14)
	ds_write2_b32 v17, v52, v53 offset1:66
	s_waitcnt vmcnt(12)
	ds_write2_b32 v17, v54, v55 offset0:132 offset1:198
	s_waitcnt vmcnt(10)
	ds_write2_b32 v21, v56, v57 offset0:8 offset1:74
	s_waitcnt vmcnt(8)
	ds_write2_b32 v21, v58, v59 offset0:140 offset1:206
	s_waitcnt vmcnt(6)
	ds_write2_b32 v22, v60, v61 offset0:16 offset1:82
	s_waitcnt vmcnt(4)
	ds_write2_b32 v22, v62, v63 offset0:148 offset1:214
	s_waitcnt vmcnt(2)
	ds_write2_b32 v23, v64, v65 offset0:24 offset1:90
	s_waitcnt vmcnt(0)
	ds_write2_b32 v23, v66, v20 offset0:156 offset1:222
	v_add_u32_e32 v17, 0x1080, v17
	s_cbranch_scc1 .LBB0_361
	s_waitcnt lgkmcnt(0)
	ds_read2_b32 v[22:23], v82 offset1:8
	ds_read2_b32 v[26:27], v82 offset0:33 offset1:41
	ds_read2_b32 v[28:29], v82 offset0:66 offset1:74
	ds_read2_b32 v[30:31], v82 offset0:99 offset1:107
	ds_read2_b32 v[32:33], v82 offset0:132 offset1:140
	ds_read2_b32 v[34:35], v82 offset0:165 offset1:173
	s_waitcnt lgkmcnt(5)
	v_bfe_u32 v2, v22, 16, 1
	v_add3_u32 v2, v22, v2, s26
	s_waitcnt lgkmcnt(4)
	v_bfe_u32 v17, v26, 16, 1
	v_lshrrev_b32_e32 v2, 16, v2
	v_add3_u32 v17, v26, v17, s26
	v_and_or_b32 v18, v17, s27, v2
	s_waitcnt lgkmcnt(3)
	v_bfe_u32 v2, v28, 16, 1
	v_add3_u32 v2, v28, v2, s26
	s_waitcnt lgkmcnt(2)
	v_bfe_u32 v17, v30, 16, 1
	ds_read2_b32 v[36:37], v82 offset0:198 offset1:206
	v_lshrrev_b32_e32 v2, 16, v2
	v_add3_u32 v17, v30, v17, s26
	ds_read2_b32 v[38:39], v82 offset0:231 offset1:239
	v_and_or_b32 v19, v17, s27, v2
	s_waitcnt lgkmcnt(3)
	v_bfe_u32 v2, v32, 16, 1
	v_add3_u32 v2, v32, v2, s26
	s_waitcnt lgkmcnt(2)
	v_bfe_u32 v17, v34, 16, 1
	v_lshrrev_b32_e32 v2, 16, v2
	v_add3_u32 v17, v34, v17, s26
	v_and_or_b32 v20, v17, s27, v2
	s_waitcnt lgkmcnt(1)
	v_bfe_u32 v2, v36, 16, 1
	v_add3_u32 v2, v36, v2, s26
	s_waitcnt lgkmcnt(0)
	v_bfe_u32 v17, v38, 16, 1
	v_lshrrev_b32_e32 v2, 16, v2
	v_add3_u32 v17, v38, v17, s26
	v_or_b32_e32 v40, s18, v81
	s_ashr_i32 s21, s20, 31
	v_and_or_b32 v21, v17, s27, v2
	v_ashrrev_i32_e32 v41, 31, v40
	v_bfe_u32 v2, v23, 16, 1
	v_lshl_add_u64 v[24:25], s[20:21], 1, v[12:13]
	v_lshlrev_b64 v[40:41], 10, v[40:41]
	v_add3_u32 v2, v23, v2, s26
	v_bfe_u32 v17, v27, 16, 1
	v_lshl_add_u64 v[40:41], v[24:25], 0, v[40:41]
	v_lshrrev_b32_e32 v2, 16, v2
	v_add3_u32 v17, v27, v17, s26
	global_store_dwordx4 v[40:41], v[18:21], off sc1
	v_or_b32_e32 v22, s18, v83
	v_ashrrev_i32_e32 v23, 31, v22
	v_and_or_b32 v18, v17, s27, v2
	v_bfe_u32 v2, v29, 16, 1
	v_add3_u32 v2, v29, v2, s26
	v_bfe_u32 v17, v31, 16, 1
	v_lshrrev_b32_e32 v2, 16, v2
	v_add3_u32 v17, v31, v17, s26
	v_and_or_b32 v19, v17, s27, v2
	v_bfe_u32 v2, v33, 16, 1
	v_add3_u32 v2, v33, v2, s26
	v_bfe_u32 v17, v35, 16, 1
	v_lshrrev_b32_e32 v2, 16, v2
	v_add3_u32 v17, v35, v17, s26
	v_and_or_b32 v20, v17, s27, v2
	v_bfe_u32 v2, v37, 16, 1
	v_add3_u32 v2, v37, v2, s26
	v_bfe_u32 v17, v39, 16, 1
	v_lshrrev_b32_e32 v2, 16, v2
	v_add3_u32 v17, v39, v17, s26
	v_lshlrev_b64 v[22:23], 10, v[22:23]
	v_and_or_b32 v21, v17, s27, v2
	ds_read2_b32 v[26:27], v82 offset0:16 offset1:24
	v_lshl_add_u64 v[22:23], v[24:25], 0, v[22:23]
	global_store_dwordx4 v[22:23], v[18:21], off sc1
	ds_read2_b32 v[22:23], v82 offset0:49 offset1:57
	ds_read2_b32 v[28:29], v82 offset0:82 offset1:90
	ds_read2_b32 v[30:31], v82 offset0:115 offset1:123
	s_waitcnt lgkmcnt(3)
	v_bfe_u32 v2, v26, 16, 1
	v_add3_u32 v2, v26, v2, s26
	s_waitcnt lgkmcnt(2)
	v_bfe_u32 v17, v22, 16, 1
	ds_read2_b32 v[32:33], v82 offset0:148 offset1:156
	v_lshrrev_b32_e32 v2, 16, v2
	v_add3_u32 v17, v22, v17, s26
	ds_read2_b32 v[34:35], v82 offset0:181 offset1:189
	v_and_or_b32 v18, v17, s27, v2
	s_waitcnt lgkmcnt(3)
	v_bfe_u32 v2, v28, 16, 1
	v_add3_u32 v2, v28, v2, s26
	s_waitcnt lgkmcnt(2)
	v_bfe_u32 v17, v30, 16, 1
	ds_read2_b32 v[36:37], v82 offset0:214 offset1:222
	v_lshrrev_b32_e32 v2, 16, v2
	v_add3_u32 v17, v30, v17, s26
	ds_read2_b32 v[38:39], v82 offset0:247 offset1:255
	v_and_or_b32 v19, v17, s27, v2
	s_waitcnt lgkmcnt(3)
	v_bfe_u32 v2, v32, 16, 1
	v_add3_u32 v2, v32, v2, s26
	s_waitcnt lgkmcnt(2)
	v_bfe_u32 v17, v34, 16, 1
	v_lshrrev_b32_e32 v2, 16, v2
	v_add3_u32 v17, v34, v17, s26
	v_and_or_b32 v20, v17, s27, v2
	s_waitcnt lgkmcnt(1)
	v_bfe_u32 v2, v36, 16, 1
	v_add3_u32 v2, v36, v2, s26
	s_waitcnt lgkmcnt(0)
	v_bfe_u32 v17, v38, 16, 1
	v_lshrrev_b32_e32 v2, 16, v2
	v_add3_u32 v17, v38, v17, s26
	v_or_b32_e32 v40, s18, v84
	v_and_or_b32 v21, v17, s27, v2
	v_ashrrev_i32_e32 v41, 31, v40
	v_bfe_u32 v2, v27, 16, 1
	v_lshlrev_b64 v[40:41], 10, v[40:41]
	v_add3_u32 v2, v27, v2, s26
	v_bfe_u32 v17, v23, 16, 1
	v_lshl_add_u64 v[40:41], v[24:25], 0, v[40:41]
	v_lshrrev_b32_e32 v2, 16, v2
	v_add3_u32 v17, v23, v17, s26
	global_store_dwordx4 v[40:41], v[18:21], off sc1
	v_or_b32_e32 v22, s18, v85
	v_ashrrev_i32_e32 v23, 31, v22
	v_and_or_b32 v18, v17, s27, v2
	v_bfe_u32 v2, v29, 16, 1
	v_add3_u32 v2, v29, v2, s26
	v_bfe_u32 v17, v31, 16, 1
	v_lshrrev_b32_e32 v2, 16, v2
	v_add3_u32 v17, v31, v17, s26
	v_and_or_b32 v19, v17, s27, v2
	v_bfe_u32 v2, v33, 16, 1
	v_add3_u32 v2, v33, v2, s26
	v_bfe_u32 v17, v35, 16, 1
	v_lshrrev_b32_e32 v2, 16, v2
	v_add3_u32 v17, v35, v17, s26
	v_and_or_b32 v20, v17, s27, v2
	v_bfe_u32 v2, v37, 16, 1
	v_add3_u32 v2, v37, v2, s26
	v_bfe_u32 v17, v39, 16, 1
	v_lshrrev_b32_e32 v2, 16, v2
	v_add3_u32 v17, v39, v17, s26
	v_lshlrev_b64 v[22:23], 10, v[22:23]
	v_and_or_b32 v21, v17, s27, v2
	v_lshl_add_u64 v[22:23], v[24:25], 0, v[22:23]
	global_store_dwordx4 v[22:23], v[18:21], off sc1
	s_waitcnt lgkmcnt(0)
	s_branch .LBB0_336

.LBB0_365:
	global_load_dwordx4 v[4:7], v[0:1], off nt
	s_add_i32 s4, s4, s6
	v_lshl_add_u64 v[0:1], v[0:1], 0, s[12:13]
	s_cmpk_lt_i32 s4, 0x4000
	s_waitcnt vmcnt(0)
	v_bfe_u32 v8, v4, 16, 1
	v_bfe_u32 v10, v6, 16, 1
	v_bfe_u32 v9, v5, 16, 1
	v_bfe_u32 v11, v7, 16, 1
	v_add3_u32 v4, v4, v8, s5
	v_add3_u32 v6, v6, v10, s5
	v_add3_u32 v5, v5, v9, s5
	v_add3_u32 v7, v7, v11, s5
	v_lshrrev_b32_e32 v4, 16, v4
	v_lshrrev_b32_e32 v6, 16, v6
	v_and_or_b32 v4, v5, s7, v4
	v_and_or_b32 v5, v7, s7, v6
	global_store_dwordx2 v[2:3], v[4:5], off sc1
	v_lshl_add_u64 v[2:3], v[2:3], 0, s[8:9]
	s_cbranch_scc1 .LBB0_365
